# last layer's FFN2 residual epilogue no longer writes the bf16 copy of x (it has no reader after the last layer); waits recounted
# speedup vs baseline: 1.0126x; 1.0075x over previous
; __device__ __forceinline__ unsigned pk2(float lo, float hi) { unsigned r; asm volatile("v_cvt_pk_bf16_f32 %0, %1, %2" : "=v"(r) : "v"(lo), "v"(hi)); return r; }
;     __device__ __forceinline__ void operator()(const f32x4 (&acc)[2][2][4][2], const Unit& u, int wr, int wc, int fr, int fq) const {
;         const int row0 = u.pm * 256 + wr * 64 + fr, col0 = u.pn * 256 + wc * 32 + 4 * fq;
;         const float* xo = (u.pm < 64) ? xoldA : (xoldB - (size_t)T_P * DM);
; #pragma unroll
;         for (int ai = 0; ai < 2; ++ai)
; #pragma unroll
;             for (int m = 0; m < 4; ++m) {
;                 const int row = row0 + ai * 128 + m * 16; const size_t ro = (size_t)row * DM + col0;
;                 float s = 0.f;
; #pragma unroll
;                 for (int bj = 0; bj < 2; ++bj)
; #pragma unroll
;                     for (int n = 0; n < 2; ++n) {
;                         const size_t o = ro + bj * 128 + n * 16;
;                         const f32x4 xn = *(const f32x4*)(xo + o) + acc[ai][bj][m][n];
;                         *(f32x4*)(xf + o) = xn;
;                         u32x2 w; w.x = pk2(xn[0], xn[1]); w.y = pk2(xn[2], xn[3]); *(u32x2*)(xb + o) = w;
;                         s += (xn[0] * xn[0] + xn[1] * xn[1]) + (xn[2] * xn[2] + xn[3] * xn[3]);
;                     }
;                 s += __shfl_xor(s, 16); s += __shfl_xor(s, 32);
;                 if (fq == 0) ssq[(size_t)row * 16 + u.pn * 4 + wc] = s;
.LBB0_2178:
	v_lshl_add_u32 v138, s42, 8, v140
	v_lshl_or_b32 v136, s40, 8, v142
	v_ashrrev_i32_e32 v139, 31, v138
	v_ashrrev_i32_e32 v137, 31, v136
	v_lshlrev_b64 v[148:149], 10, v[138:139]
	s_cmp_lt_i32 s42, 64
	v_lshl_add_u64 v[152:153], v[148:149], 0, v[136:137]
	s_cselect_b32 s13, s17, -1
	s_cselect_b32 s12, s16, 0xfc000000
	v_lshlrev_b64 v[154:155], 2, v[152:153]
	v_lshl_add_u64 v[156:157], s[12:13], 0, v[154:155]
	v_subrev_u32_e32 v162, s12, v156
	v_add_u32_e32 v163, 0x0, v162
	global_load_dwordx4 v[170:173], v163, s[12:13]
	v_add_u32_e32 v163, 0x40, v162
	global_load_dwordx4 v[174:177], v163, s[12:13]
	v_add_u32_e32 v163, 0x200, v162
	global_load_dwordx4 v[178:181], v163, s[12:13]
	v_add_u32_e32 v163, 0x240, v162
	global_load_dwordx4 v[182:185], v163, s[12:13]
	v_add_u32_e32 v163, 0x10000, v162
	global_load_dwordx4 v[186:189], v163, s[12:13]
	v_add_u32_e32 v163, 0x10040, v162
	global_load_dwordx4 v[190:193], v163, s[12:13]
	v_add_u32_e32 v163, 0x10200, v162
	global_load_dwordx4 v[194:197], v163, s[12:13]
	v_add_u32_e32 v163, 0x10240, v162
	global_load_dwordx4 v[198:201], v163, s[12:13]
	v_add_u32_e32 v163, 0x20000, v162
	global_load_dwordx4 v[202:205], v163, s[12:13]
	v_add_u32_e32 v163, 0x20040, v162
	global_load_dwordx4 v[206:209], v163, s[12:13]
	v_add_u32_e32 v163, 0x20200, v162
	global_load_dwordx4 v[210:213], v163, s[12:13]
	v_add_u32_e32 v163, 0x20240, v162
	global_load_dwordx4 v[232:235], v163, s[12:13]
	v_add_u32_e32 v163, 0x30000, v162
	global_load_dwordx4 v[236:239], v163, s[12:13]
	v_add_u32_e32 v163, 0x30040, v162
	global_load_dwordx4 v[240:243], v163, s[12:13]
	v_add_u32_e32 v163, 0x30200, v162
	global_load_dwordx4 v[244:247], v163, s[12:13]
	v_add_u32_e32 v163, 0x30240, v162
	global_load_dwordx4 v[248:251], v163, s[12:13]
	v_add_u32_e32 v163, 0x80000, v162
	global_load_dwordx4 v[252:255], v163, s[12:13]
	v_lshl_add_u64 v[158:159], v[152:153], 1, s[22:23]
	v_lshl_add_u64 v[160:161], s[16:17], 0, v[154:155]
	v_xor_b32_e32 v147, 32, v146
	s_lshl_b32 s40, s40, 2
	s_ashr_i32 s41, s40, 31
	s_waitcnt vmcnt(16)
	v_mov_b32_e32 v148, v170
	v_mov_b32_e32 v149, v171
	v_mov_b32_e32 v150, v172
	v_mov_b32_e32 v151, v173
	v_add_u32_e32 v163, 0x80040, v162
	global_load_dwordx4 v[170:173], v163, s[12:13]
	v_pk_add_f32 v[126:127], v[126:127], v[150:151]
	v_pk_add_f32 v[124:125], v[124:125], v[148:149]
	global_store_dwordx4 v[160:161], v[124:127], off
	v_cvt_pk_bf16_f32 v148, v124, v125
	v_cvt_pk_bf16_f32 v149, v126, v127
	s_waitcnt vmcnt(17)
	v_mov_b32_e32 v148, v174
	v_mov_b32_e32 v149, v175
	v_mov_b32_e32 v150, v176
	v_mov_b32_e32 v151, v177
	v_add_u32_e32 v163, 0x80200, v162
	global_load_dwordx4 v[174:177], v163, s[12:13]
	v_pk_add_f32 v[122:123], v[122:123], v[150:151]
	v_pk_add_f32 v[120:121], v[120:121], v[148:149]
	global_store_dwordx4 v[160:161], v[120:123], off offset:64
	v_cvt_pk_bf16_f32 v148, v120, v121
	v_cvt_pk_bf16_f32 v149, v122, v123
	s_waitcnt vmcnt(18)
	v_mov_b32_e32 v148, v178
	v_mov_b32_e32 v149, v179
	v_mov_b32_e32 v150, v180
	v_mov_b32_e32 v151, v181
	v_add_u32_e32 v163, 0x80240, v162
	global_load_dwordx4 v[178:181], v163, s[12:13]
	v_pk_add_f32 v[150:151], v[118:119], v[150:151]
	v_pk_add_f32 v[148:149], v[116:117], v[148:149]
	global_store_dwordx4 v[160:161], v[148:151], off offset:512
	v_cvt_pk_bf16_f32 v116, v148, v149
	v_cvt_pk_bf16_f32 v117, v150, v151
	v_mul_f32_e32 v118, v125, v125
	v_mul_f32_e32 v119, v127, v127
	v_fmac_f32_e32 v118, v124, v124
	v_fmac_f32_e32 v119, v126, v126
	v_add_f32_e32 v118, v118, v119
	v_mul_f32_e32 v119, v121, v121
	v_mul_f32_e32 v121, v123, v123
	v_fmac_f32_e32 v119, v120, v120
	v_fmac_f32_e32 v121, v122, v122
	v_add_f32_e32 v119, v119, v121
	v_add_f32_e32 v118, v118, v119
	v_mul_f32_e32 v119, v149, v149
	v_mul_f32_e32 v120, v151, v151
	v_fmac_f32_e32 v119, v148, v148
	v_fmac_f32_e32 v120, v150, v150
	v_add_f32_e32 v119, v119, v120
	v_and_b32_e32 v117, 64, v146
	v_add_f32_e32 v122, v118, v119
	v_xor_b32_e32 v116, 16, v146
	v_add_u32_e32 v117, 64, v117
	v_cmp_lt_i32_e32 vcc, v116, v117
	s_waitcnt vmcnt(19)
	v_mov_b32_e32 v152, v182
	v_mov_b32_e32 v153, v183
	v_mov_b32_e32 v154, v184
	v_mov_b32_e32 v155, v185
	v_add_u32_e32 v163, 0x90000, v162
	global_load_dwordx4 v[182:185], v163, s[12:13]
	v_pk_add_f32 v[120:121], v[114:115], v[154:155]
	v_pk_add_f32 v[118:119], v[112:113], v[152:153]
	v_mul_f32_e32 v113, v121, v121
	v_mul_f32_e32 v112, v119, v119
	v_fmac_f32_e32 v112, v118, v118
	v_fmac_f32_e32 v113, v120, v120
	v_cndmask_b32_e32 v116, v146, v116, vcc
	v_add_f32_e32 v112, v112, v113
	v_lshlrev_b32_e32 v116, 2, v116
	v_add_f32_e32 v112, v122, v112
	ds_bpermute_b32 v113, v116, v112
	v_cmp_lt_i32_e32 vcc, v147, v117
	global_store_dwordx4 v[160:161], v[118:121], off offset:576
	s_waitcnt lgkmcnt(0)
	v_add_f32_e32 v112, v112, v113
	v_cndmask_b32_e32 v114, v146, v147, vcc
	v_lshlrev_b32_e32 v114, 2, v114
	ds_bpermute_b32 v113, v114, v112
	v_cvt_pk_bf16_f32 v118, v118, v119
	v_cvt_pk_bf16_f32 v119, v120, v121
	s_and_saveexec_b64 s[42:43], s[8:9]
	s_cbranch_execz .LBB0_2180
	s_waitcnt lgkmcnt(0)
	v_add_f32_e32 v115, v112, v113
	v_lshlrev_b64 v[112:113], 6, v[138:139]
	v_lshl_add_u64 v[112:113], s[24:25], 0, v[112:113]
	v_lshl_add_u64 v[112:113], s[40:41], 2, v[112:113]
	s_lshl_b32 s26, s74, 2
	v_lshl_add_u64 v[112:113], v[112:113], 0, s[26:27]
	global_store_dword v[112:113], v115, off
; __device__ __forceinline__ unsigned pk2(float lo, float hi) { unsigned r; asm volatile("v_cvt_pk_bf16_f32 %0, %1, %2" : "=v"(r) : "v"(lo), "v"(hi)); return r; }
;     __device__ __forceinline__ void operator()(const f32x4 (&acc)[2][2][4][2], const Unit& u, int wr, int wc, int fr, int fq) const {
;     ...
;             for (int m = 0; m < 4; ++m) {
;                 const int row = row0 + ai * 128 + m * 16; const size_t ro = (size_t)row * DM + col0;
;                 float s = 0.f;
; #pragma unroll
;                 for (int bj = 0; bj < 2; ++bj)
; #pragma unroll
;                     for (int n = 0; n < 2; ++n) {
;                         const size_t o = ro + bj * 128 + n * 16;
;                         const f32x4 xn = *(const f32x4*)(xo + o) + acc[ai][bj][m][n];
;                         *(f32x4*)(xf + o) = xn;
;                         u32x2 w; w.x = pk2(xn[0], xn[1]); w.y = pk2(xn[2], xn[3]); *(u32x2*)(xb + o) = w;
;                         s += (xn[0] * xn[0] + xn[1] * xn[1]) + (xn[2] * xn[2] + xn[3] * xn[3]);
;                     }
;                 s += __shfl_xor(s, 16); s += __shfl_xor(s, 32);
;                 if (fq == 0) ssq[(size_t)row * 16 + u.pn * 4 + wc] = s;
.LBB0_2180:
	s_or_b64 exec, exec, s[42:43]
	v_or_b32_e32 v112, 16, v138
	s_waitcnt lgkmcnt(0)
	v_ashrrev_i32_e32 v113, 31, v112
	v_lshlrev_b64 v[118:119], 10, v[112:113]
	v_lshl_add_u64 v[122:123], v[118:119], 0, v[136:137]
	v_lshlrev_b64 v[124:125], 2, v[122:123]
	v_lshl_add_u64 v[126:127], s[12:13], 0, v[124:125]
	v_lshl_add_u64 v[122:123], v[122:123], 1, s[22:23]
	v_lshl_add_u64 v[124:125], s[16:17], 0, v[124:125]
	s_waitcnt vmcnt(20)
	v_mov_b32_e32 v118, v186
	v_mov_b32_e32 v119, v187
	v_mov_b32_e32 v120, v188
	v_mov_b32_e32 v121, v189
	v_add_u32_e32 v163, 0x90040, v162
	global_load_dwordx4 v[186:189], v163, s[12:13]
	v_pk_add_f32 v[110:111], v[110:111], v[120:121]
	v_pk_add_f32 v[108:109], v[108:109], v[118:119]
	global_store_dwordx4 v[124:125], v[108:111], off
	v_cvt_pk_bf16_f32 v118, v108, v109
	v_cvt_pk_bf16_f32 v119, v110, v111
	v_mul_f32_e32 v109, v109, v109
	v_mul_f32_e32 v111, v111, v111
	v_fmac_f32_e32 v109, v108, v108
	v_fmac_f32_e32 v111, v110, v110
	v_add_f32_e32 v108, v109, v111
	s_waitcnt vmcnt(21)
	v_mov_b32_e32 v118, v190
	v_mov_b32_e32 v119, v191
	v_mov_b32_e32 v120, v192
	v_mov_b32_e32 v121, v193
	v_add_u32_e32 v163, 0x90200, v162
	global_load_dwordx4 v[190:193], v163, s[12:13]
	v_pk_add_f32 v[106:107], v[106:107], v[120:121]
	v_pk_add_f32 v[104:105], v[104:105], v[118:119]
	global_store_dwordx4 v[124:125], v[104:107], off offset:64
	v_cvt_pk_bf16_f32 v118, v104, v105
	v_cvt_pk_bf16_f32 v119, v106, v107
	v_mul_f32_e32 v105, v105, v105
	v_mul_f32_e32 v107, v107, v107
	v_fmac_f32_e32 v105, v104, v104
	v_fmac_f32_e32 v107, v106, v106
	v_add_f32_e32 v104, v105, v107
	v_add_f32_e32 v104, v108, v104
	s_waitcnt vmcnt(22)
	v_mov_b32_e32 v118, v194
	v_mov_b32_e32 v119, v195
	v_mov_b32_e32 v120, v196
	v_mov_b32_e32 v121, v197
	v_add_u32_e32 v163, 0x90240, v162
	global_load_dwordx4 v[194:197], v163, s[12:13]
	v_pk_add_f32 v[102:103], v[102:103], v[120:121]
	v_pk_add_f32 v[100:101], v[100:101], v[118:119]
	global_store_dwordx4 v[124:125], v[100:103], off offset:512
	v_cvt_pk_bf16_f32 v118, v100, v101
	v_cvt_pk_bf16_f32 v119, v102, v103
	v_mul_f32_e32 v101, v101, v101
	v_mul_f32_e32 v103, v103, v103
	v_fmac_f32_e32 v101, v100, v100
	v_fmac_f32_e32 v103, v102, v102
	v_add_f32_e32 v100, v101, v103
	v_add_f32_e32 v102, v104, v100
	s_waitcnt vmcnt(23)
	v_mov_b32_e32 v118, v198
	v_mov_b32_e32 v119, v199
	v_mov_b32_e32 v120, v200
	v_mov_b32_e32 v121, v201
	v_add_u32_e32 v163, 0xa0000, v162
	global_load_dwordx4 v[198:201], v163, s[12:13]
	v_pk_add_f32 v[100:101], v[98:99], v[120:121]
	v_pk_add_f32 v[98:99], v[96:97], v[118:119]
	v_mul_f32_e32 v97, v101, v101
	v_mul_f32_e32 v96, v99, v99
	v_fmac_f32_e32 v96, v98, v98
	v_fmac_f32_e32 v97, v100, v100
	v_add_f32_e32 v96, v96, v97
	v_add_f32_e32 v96, v102, v96
	ds_bpermute_b32 v97, v116, v96
	global_store_dwordx4 v[124:125], v[98:101], off offset:576
	s_waitcnt lgkmcnt(0)
	v_add_f32_e32 v96, v96, v97
	ds_bpermute_b32 v97, v114, v96
	v_cvt_pk_bf16_f32 v98, v98, v99
	v_cvt_pk_bf16_f32 v99, v100, v101
	s_and_saveexec_b64 s[42:43], s[8:9]
	s_cbranch_execz .LBB0_2182
	s_waitcnt lgkmcnt(0)
	v_add_f32_e32 v98, v96, v97
	v_lshlrev_b64 v[96:97], 6, v[112:113]
	v_lshl_add_u64 v[96:97], s[24:25], 0, v[96:97]
	v_lshl_add_u64 v[96:97], s[40:41], 2, v[96:97]
	s_lshl_b32 s26, s74, 2
	v_lshl_add_u64 v[96:97], v[96:97], 0, s[26:27]
	global_store_dword v[96:97], v98, off
.LBB0_2182:
	s_or_b64 exec, exec, s[42:43]
	v_or_b32_e32 v96, 32, v138
	s_waitcnt lgkmcnt(0)
	v_ashrrev_i32_e32 v97, 31, v96
	v_lshlrev_b64 v[98:99], 10, v[96:97]
	v_lshl_add_u64 v[102:103], v[98:99], 0, v[136:137]
	v_lshlrev_b64 v[104:105], 2, v[102:103]
	v_lshl_add_u64 v[106:107], s[12:13], 0, v[104:105]
	v_lshl_add_u64 v[102:103], v[102:103], 1, s[22:23]
	v_lshl_add_u64 v[104:105], s[16:17], 0, v[104:105]
	s_waitcnt vmcnt(24)
	v_mov_b32_e32 v98, v202
	v_mov_b32_e32 v99, v203
	v_mov_b32_e32 v100, v204
	v_mov_b32_e32 v101, v205
	v_add_u32_e32 v163, 0xa0040, v162
	global_load_dwordx4 v[202:205], v163, s[12:13]
	v_pk_add_f32 v[94:95], v[94:95], v[100:101]
	v_pk_add_f32 v[92:93], v[92:93], v[98:99]
	global_store_dwordx4 v[104:105], v[92:95], off
	v_cvt_pk_bf16_f32 v98, v92, v93
	v_cvt_pk_bf16_f32 v99, v94, v95
	v_mul_f32_e32 v93, v93, v93
	v_mul_f32_e32 v95, v95, v95
	v_fmac_f32_e32 v93, v92, v92
	v_fmac_f32_e32 v95, v94, v94
	v_add_f32_e32 v92, v93, v95
	s_waitcnt vmcnt(25)
	v_mov_b32_e32 v98, v206
	v_mov_b32_e32 v99, v207
	v_mov_b32_e32 v100, v208
	v_mov_b32_e32 v101, v209
	v_add_u32_e32 v163, 0xa0200, v162
	global_load_dwordx4 v[206:209], v163, s[12:13]
	v_pk_add_f32 v[90:91], v[90:91], v[100:101]
	v_pk_add_f32 v[88:89], v[88:89], v[98:99]
	global_store_dwordx4 v[104:105], v[88:91], off offset:64
	v_cvt_pk_bf16_f32 v98, v88, v89
	v_cvt_pk_bf16_f32 v99, v90, v91
	v_mul_f32_e32 v89, v89, v89
	v_mul_f32_e32 v91, v91, v91
	v_fmac_f32_e32 v89, v88, v88
	v_fmac_f32_e32 v91, v90, v90
	v_add_f32_e32 v88, v89, v91
	v_add_f32_e32 v88, v92, v88
	s_waitcnt vmcnt(26)
	v_mov_b32_e32 v98, v210
	v_mov_b32_e32 v99, v211
	v_mov_b32_e32 v100, v212
	v_mov_b32_e32 v101, v213
	v_add_u32_e32 v163, 0xa0240, v162
	global_load_dwordx4 v[210:213], v163, s[12:13]
	v_pk_add_f32 v[86:87], v[86:87], v[100:101]
	v_pk_add_f32 v[84:85], v[84:85], v[98:99]
	global_store_dwordx4 v[104:105], v[84:87], off offset:512
	v_cvt_pk_bf16_f32 v98, v84, v85
	v_cvt_pk_bf16_f32 v99, v86, v87
	v_mul_f32_e32 v85, v85, v85
	v_mul_f32_e32 v87, v87, v87
	v_fmac_f32_e32 v85, v84, v84
	v_fmac_f32_e32 v87, v86, v86
	v_add_f32_e32 v84, v85, v87
	v_add_f32_e32 v86, v88, v84
	s_waitcnt vmcnt(27)
	v_mov_b32_e32 v98, v232
	v_mov_b32_e32 v99, v233
	v_mov_b32_e32 v100, v234
	v_mov_b32_e32 v101, v235
	v_add_u32_e32 v163, 0xb0000, v162
	global_load_dwordx4 v[232:235], v163, s[12:13]
	v_pk_add_f32 v[84:85], v[82:83], v[100:101]
	v_pk_add_f32 v[82:83], v[80:81], v[98:99]
	v_mul_f32_e32 v81, v85, v85
	v_mul_f32_e32 v80, v83, v83
	v_fmac_f32_e32 v80, v82, v82
	v_fmac_f32_e32 v81, v84, v84
	v_add_f32_e32 v80, v80, v81
	v_add_f32_e32 v80, v86, v80
	ds_bpermute_b32 v81, v116, v80
	global_store_dwordx4 v[104:105], v[82:85], off offset:576
	s_waitcnt lgkmcnt(0)
	v_add_f32_e32 v80, v80, v81
	ds_bpermute_b32 v81, v114, v80
	v_cvt_pk_bf16_f32 v82, v82, v83
	v_cvt_pk_bf16_f32 v83, v84, v85
	s_and_saveexec_b64 s[42:43], s[8:9]
	s_cbranch_execz .LBB0_2184
	s_waitcnt lgkmcnt(0)
	v_add_f32_e32 v82, v80, v81
	v_lshlrev_b64 v[80:81], 6, v[96:97]
	v_lshl_add_u64 v[80:81], s[24:25], 0, v[80:81]
	v_lshl_add_u64 v[80:81], s[40:41], 2, v[80:81]
	s_lshl_b32 s26, s74, 2
	v_lshl_add_u64 v[80:81], v[80:81], 0, s[26:27]
	global_store_dword v[80:81], v82, off
; __device__ __forceinline__ unsigned pk2(float lo, float hi) { unsigned r; asm volatile("v_cvt_pk_bf16_f32 %0, %1, %2" : "=v"(r) : "v"(lo), "v"(hi)); return r; }
;     __device__ __forceinline__ void operator()(const f32x4 (&acc)[2][2][4][2], const Unit& u, int wr, int wc, int fr, int fq) const {
;     ...
;             for (int m = 0; m < 4; ++m) {
;                 const int row = row0 + ai * 128 + m * 16; const size_t ro = (size_t)row * DM + col0;
;                 float s = 0.f;
; #pragma unroll
;                 for (int bj = 0; bj < 2; ++bj)
; #pragma unroll
;                     for (int n = 0; n < 2; ++n) {
;                         const size_t o = ro + bj * 128 + n * 16;
;                         const f32x4 xn = *(const f32x4*)(xo + o) + acc[ai][bj][m][n];
;                         *(f32x4*)(xf + o) = xn;
;                         u32x2 w; w.x = pk2(xn[0], xn[1]); w.y = pk2(xn[2], xn[3]); *(u32x2*)(xb + o) = w;
;                         s += (xn[0] * xn[0] + xn[1] * xn[1]) + (xn[2] * xn[2] + xn[3] * xn[3]);
;                     }
;                 s += __shfl_xor(s, 16); s += __shfl_xor(s, 32);
;                 if (fq == 0) ssq[(size_t)row * 16 + u.pn * 4 + wc] = s;
.LBB0_2184:
	s_or_b64 exec, exec, s[42:43]
	v_or_b32_e32 v80, 48, v138
	s_waitcnt lgkmcnt(0)
	v_ashrrev_i32_e32 v81, 31, v80
	v_lshlrev_b64 v[82:83], 10, v[80:81]
	v_lshl_add_u64 v[86:87], v[82:83], 0, v[136:137]
	v_lshlrev_b64 v[88:89], 2, v[86:87]
	v_lshl_add_u64 v[90:91], s[12:13], 0, v[88:89]
	v_lshl_add_u64 v[86:87], v[86:87], 1, s[22:23]
	v_lshl_add_u64 v[88:89], s[16:17], 0, v[88:89]
	s_waitcnt vmcnt(28)
	v_mov_b32_e32 v82, v236
	v_mov_b32_e32 v83, v237
	v_mov_b32_e32 v84, v238
	v_mov_b32_e32 v85, v239
	v_add_u32_e32 v163, 0xb0040, v162
	global_load_dwordx4 v[236:239], v163, s[12:13]
	v_pk_add_f32 v[78:79], v[78:79], v[84:85]
	v_pk_add_f32 v[76:77], v[76:77], v[82:83]
	global_store_dwordx4 v[88:89], v[76:79], off
	v_cvt_pk_bf16_f32 v82, v76, v77
	v_cvt_pk_bf16_f32 v83, v78, v79
	v_mul_f32_e32 v77, v77, v77
	v_mul_f32_e32 v79, v79, v79
	v_fmac_f32_e32 v77, v76, v76
	v_fmac_f32_e32 v79, v78, v78
	v_add_f32_e32 v76, v77, v79
	s_waitcnt vmcnt(29)
	v_mov_b32_e32 v82, v240
	v_mov_b32_e32 v83, v241
	v_mov_b32_e32 v84, v242
	v_mov_b32_e32 v85, v243
	v_add_u32_e32 v163, 0xb0200, v162
	global_load_dwordx4 v[240:243], v163, s[12:13]
	v_pk_add_f32 v[74:75], v[74:75], v[84:85]
	v_pk_add_f32 v[72:73], v[72:73], v[82:83]
	global_store_dwordx4 v[88:89], v[72:75], off offset:64
	v_cvt_pk_bf16_f32 v82, v72, v73
	v_cvt_pk_bf16_f32 v83, v74, v75
	v_mul_f32_e32 v73, v73, v73
	v_mul_f32_e32 v75, v75, v75
	v_fmac_f32_e32 v73, v72, v72
	v_fmac_f32_e32 v75, v74, v74
	v_add_f32_e32 v72, v73, v75
	v_add_f32_e32 v72, v76, v72
	s_waitcnt vmcnt(30)
	v_mov_b32_e32 v82, v244
	v_mov_b32_e32 v83, v245
	v_mov_b32_e32 v84, v246
	v_mov_b32_e32 v85, v247
	v_add_u32_e32 v163, 0xb0240, v162
	global_load_dwordx4 v[244:247], v163, s[12:13]
	v_pk_add_f32 v[70:71], v[70:71], v[84:85]
	v_pk_add_f32 v[68:69], v[68:69], v[82:83]
	global_store_dwordx4 v[88:89], v[68:71], off offset:512
	v_cvt_pk_bf16_f32 v82, v68, v69
	v_cvt_pk_bf16_f32 v83, v70, v71
	v_mul_f32_e32 v69, v69, v69
	v_mul_f32_e32 v71, v71, v71
	v_fmac_f32_e32 v69, v68, v68
	v_fmac_f32_e32 v71, v70, v70
	v_add_f32_e32 v68, v69, v71
	v_add_f32_e32 v70, v72, v68
	s_waitcnt vmcnt(31)
	v_mov_b32_e32 v82, v248
	v_mov_b32_e32 v83, v249
	v_mov_b32_e32 v84, v250
	v_mov_b32_e32 v85, v251
	v_pk_add_f32 v[68:69], v[66:67], v[84:85]
	v_pk_add_f32 v[66:67], v[64:65], v[82:83]
	v_mul_f32_e32 v65, v69, v69
	v_mul_f32_e32 v64, v67, v67
	v_fmac_f32_e32 v64, v66, v66
	v_fmac_f32_e32 v65, v68, v68
	v_add_f32_e32 v64, v64, v65
	v_add_f32_e32 v64, v70, v64
	ds_bpermute_b32 v65, v116, v64
	global_store_dwordx4 v[88:89], v[66:69], off offset:576
	s_waitcnt lgkmcnt(0)
	v_add_f32_e32 v64, v64, v65
	ds_bpermute_b32 v65, v114, v64
	v_cvt_pk_bf16_f32 v66, v66, v67
	v_cvt_pk_bf16_f32 v67, v68, v69
	s_and_saveexec_b64 s[42:43], s[8:9]
	s_cbranch_execz .LBB0_2186
	s_waitcnt lgkmcnt(0)
	v_add_f32_e32 v66, v64, v65
	v_lshlrev_b64 v[64:65], 6, v[80:81]
	v_lshl_add_u64 v[64:65], s[24:25], 0, v[64:65]
	v_lshl_add_u64 v[64:65], s[40:41], 2, v[64:65]
	s_lshl_b32 s26, s74, 2
	v_lshl_add_u64 v[64:65], v[64:65], 0, s[26:27]
	global_store_dword v[64:65], v66, off
.LBB0_2186:
	s_or_b64 exec, exec, s[42:43]
	v_add_u32_e32 v64, 0x80, v138
	s_waitcnt lgkmcnt(0)
	v_ashrrev_i32_e32 v65, 31, v64
	v_lshlrev_b64 v[66:67], 10, v[64:65]
	v_lshl_add_u64 v[70:71], v[66:67], 0, v[136:137]
	v_lshlrev_b64 v[72:73], 2, v[70:71]
	v_lshl_add_u64 v[74:75], s[12:13], 0, v[72:73]
	v_lshl_add_u64 v[70:71], v[70:71], 1, s[22:23]
	v_lshl_add_u64 v[72:73], s[16:17], 0, v[72:73]
	s_waitcnt vmcnt(31)
	v_mov_b32_e32 v66, v252
	v_mov_b32_e32 v67, v253
	v_mov_b32_e32 v68, v254
	v_mov_b32_e32 v69, v255
	v_pk_add_f32 v[62:63], v[62:63], v[68:69]
	v_pk_add_f32 v[60:61], v[60:61], v[66:67]
	global_store_dwordx4 v[72:73], v[60:63], off
	v_cvt_pk_bf16_f32 v66, v60, v61
	v_cvt_pk_bf16_f32 v67, v62, v63
	v_mul_f32_e32 v61, v61, v61
	v_mul_f32_e32 v63, v63, v63
	v_fmac_f32_e32 v61, v60, v60
	v_fmac_f32_e32 v63, v62, v62
	v_add_f32_e32 v60, v61, v63
	s_waitcnt vmcnt(31)
	v_mov_b32_e32 v66, v170
	v_mov_b32_e32 v67, v171
	v_mov_b32_e32 v68, v172
	v_mov_b32_e32 v69, v173
	v_pk_add_f32 v[58:59], v[58:59], v[68:69]
	v_pk_add_f32 v[56:57], v[56:57], v[66:67]
	global_store_dwordx4 v[72:73], v[56:59], off offset:64
	v_cvt_pk_bf16_f32 v66, v56, v57
	v_cvt_pk_bf16_f32 v67, v58, v59
	v_mul_f32_e32 v57, v57, v57
	v_mul_f32_e32 v59, v59, v59
	v_fmac_f32_e32 v57, v56, v56
	v_fmac_f32_e32 v59, v58, v58
	v_add_f32_e32 v56, v57, v59
	v_add_f32_e32 v56, v60, v56
	s_waitcnt vmcnt(30)
	v_mov_b32_e32 v66, v174
	v_mov_b32_e32 v67, v175
	v_mov_b32_e32 v68, v176
	v_mov_b32_e32 v69, v177
	v_pk_add_f32 v[54:55], v[54:55], v[68:69]
	v_pk_add_f32 v[52:53], v[52:53], v[66:67]
	global_store_dwordx4 v[72:73], v[52:55], off offset:512
	v_cvt_pk_bf16_f32 v66, v52, v53
	v_cvt_pk_bf16_f32 v67, v54, v55
	v_mul_f32_e32 v53, v53, v53
	v_mul_f32_e32 v55, v55, v55
	v_fmac_f32_e32 v53, v52, v52
	v_fmac_f32_e32 v55, v54, v54
	v_add_f32_e32 v52, v53, v55
	v_add_f32_e32 v54, v56, v52
	s_waitcnt vmcnt(29)
	v_mov_b32_e32 v66, v178
	v_mov_b32_e32 v67, v179
	v_mov_b32_e32 v68, v180
	v_mov_b32_e32 v69, v181
	v_pk_add_f32 v[52:53], v[50:51], v[68:69]
	v_pk_add_f32 v[50:51], v[48:49], v[66:67]
	v_mul_f32_e32 v49, v53, v53
	v_mul_f32_e32 v48, v51, v51
	v_fmac_f32_e32 v48, v50, v50
	v_fmac_f32_e32 v49, v52, v52
	v_add_f32_e32 v48, v48, v49
	v_add_f32_e32 v48, v54, v48
	ds_bpermute_b32 v49, v116, v48
	global_store_dwordx4 v[72:73], v[50:53], off offset:576
	s_waitcnt lgkmcnt(0)
	v_add_f32_e32 v48, v48, v49
	ds_bpermute_b32 v49, v114, v48
	v_cvt_pk_bf16_f32 v50, v50, v51
	v_cvt_pk_bf16_f32 v51, v52, v53
	s_and_saveexec_b64 s[42:43], s[8:9]
	s_cbranch_execz .LBB0_2188
	s_waitcnt lgkmcnt(0)
	v_add_f32_e32 v50, v48, v49
	v_lshlrev_b64 v[48:49], 6, v[64:65]
	v_lshl_add_u64 v[48:49], s[24:25], 0, v[48:49]
	v_lshl_add_u64 v[48:49], s[40:41], 2, v[48:49]
	s_lshl_b32 s26, s74, 2
	v_lshl_add_u64 v[48:49], v[48:49], 0, s[26:27]
	global_store_dword v[48:49], v50, off
; __device__ __forceinline__ unsigned pk2(float lo, float hi) { unsigned r; asm volatile("v_cvt_pk_bf16_f32 %0, %1, %2" : "=v"(r) : "v"(lo), "v"(hi)); return r; }
;     __device__ __forceinline__ void operator()(const f32x4 (&acc)[2][2][4][2], const Unit& u, int wr, int wc, int fr, int fq) const {
;     ...
;             for (int m = 0; m < 4; ++m) {
;                 const int row = row0 + ai * 128 + m * 16; const size_t ro = (size_t)row * DM + col0;
;                 float s = 0.f;
; #pragma unroll
;                 for (int bj = 0; bj < 2; ++bj)
; #pragma unroll
;                     for (int n = 0; n < 2; ++n) {
;                         const size_t o = ro + bj * 128 + n * 16;
;                         const f32x4 xn = *(const f32x4*)(xo + o) + acc[ai][bj][m][n];
;                         *(f32x4*)(xf + o) = xn;
;                         u32x2 w; w.x = pk2(xn[0], xn[1]); w.y = pk2(xn[2], xn[3]); *(u32x2*)(xb + o) = w;
;                         s += (xn[0] * xn[0] + xn[1] * xn[1]) + (xn[2] * xn[2] + xn[3] * xn[3]);
;                     }
;                 s += __shfl_xor(s, 16); s += __shfl_xor(s, 32);
;                 if (fq == 0) ssq[(size_t)row * 16 + u.pn * 4 + wc] = s;
.LBB0_2188:
	s_or_b64 exec, exec, s[42:43]
	v_add_u32_e32 v48, 0x90, v138
	s_waitcnt lgkmcnt(0)
	v_ashrrev_i32_e32 v49, 31, v48
	v_lshlrev_b64 v[50:51], 10, v[48:49]
	v_lshl_add_u64 v[54:55], v[50:51], 0, v[136:137]
	v_lshlrev_b64 v[56:57], 2, v[54:55]
	v_lshl_add_u64 v[58:59], s[12:13], 0, v[56:57]
	v_lshl_add_u64 v[54:55], v[54:55], 1, s[22:23]
	v_lshl_add_u64 v[56:57], s[16:17], 0, v[56:57]
	s_waitcnt vmcnt(28)
	v_mov_b32_e32 v50, v182
	v_mov_b32_e32 v51, v183
	v_mov_b32_e32 v52, v184
	v_mov_b32_e32 v53, v185
	v_pk_add_f32 v[46:47], v[46:47], v[52:53]
	v_pk_add_f32 v[44:45], v[44:45], v[50:51]
	global_store_dwordx4 v[56:57], v[44:47], off
	v_cvt_pk_bf16_f32 v50, v44, v45
	v_cvt_pk_bf16_f32 v51, v46, v47
	v_mul_f32_e32 v45, v45, v45
	v_mul_f32_e32 v47, v47, v47
	v_fmac_f32_e32 v45, v44, v44
	v_fmac_f32_e32 v47, v46, v46
	v_add_f32_e32 v44, v45, v47
	s_waitcnt vmcnt(27)
	v_mov_b32_e32 v50, v186
	v_mov_b32_e32 v51, v187
	v_mov_b32_e32 v52, v188
	v_mov_b32_e32 v53, v189
	v_pk_add_f32 v[42:43], v[42:43], v[52:53]
	v_pk_add_f32 v[40:41], v[40:41], v[50:51]
	global_store_dwordx4 v[56:57], v[40:43], off offset:64
	v_cvt_pk_bf16_f32 v50, v40, v41
	v_cvt_pk_bf16_f32 v51, v42, v43
	v_mul_f32_e32 v41, v41, v41
	v_mul_f32_e32 v43, v43, v43
	v_fmac_f32_e32 v41, v40, v40
	v_fmac_f32_e32 v43, v42, v42
	v_add_f32_e32 v40, v41, v43
	v_add_f32_e32 v40, v44, v40
	s_waitcnt vmcnt(26)
	v_mov_b32_e32 v50, v190
	v_mov_b32_e32 v51, v191
	v_mov_b32_e32 v52, v192
	v_mov_b32_e32 v53, v193
	v_pk_add_f32 v[38:39], v[38:39], v[52:53]
	v_pk_add_f32 v[36:37], v[36:37], v[50:51]
	global_store_dwordx4 v[56:57], v[36:39], off offset:512
	v_cvt_pk_bf16_f32 v50, v36, v37
	v_cvt_pk_bf16_f32 v51, v38, v39
	v_mul_f32_e32 v37, v37, v37
	v_mul_f32_e32 v39, v39, v39
	v_fmac_f32_e32 v37, v36, v36
	v_fmac_f32_e32 v39, v38, v38
	v_add_f32_e32 v36, v37, v39
	v_add_f32_e32 v38, v40, v36
	s_waitcnt vmcnt(25)
	v_mov_b32_e32 v50, v194
	v_mov_b32_e32 v51, v195
	v_mov_b32_e32 v52, v196
	v_mov_b32_e32 v53, v197
	v_pk_add_f32 v[36:37], v[34:35], v[52:53]
	v_pk_add_f32 v[34:35], v[32:33], v[50:51]
	v_mul_f32_e32 v33, v37, v37
	v_mul_f32_e32 v32, v35, v35
	v_fmac_f32_e32 v32, v34, v34
	v_fmac_f32_e32 v33, v36, v36
	v_add_f32_e32 v32, v32, v33
	v_add_f32_e32 v32, v38, v32
	ds_bpermute_b32 v33, v116, v32
	global_store_dwordx4 v[56:57], v[34:37], off offset:576
	s_waitcnt lgkmcnt(0)
	v_add_f32_e32 v32, v32, v33
	ds_bpermute_b32 v33, v114, v32
	v_cvt_pk_bf16_f32 v34, v34, v35
	v_cvt_pk_bf16_f32 v35, v36, v37
	s_and_saveexec_b64 s[42:43], s[8:9]
	s_cbranch_execz .LBB0_2190
	s_waitcnt lgkmcnt(0)
	v_add_f32_e32 v34, v32, v33
	v_lshlrev_b64 v[32:33], 6, v[48:49]
	v_lshl_add_u64 v[32:33], s[24:25], 0, v[32:33]
	v_lshl_add_u64 v[32:33], s[40:41], 2, v[32:33]
	s_lshl_b32 s26, s74, 2
	v_lshl_add_u64 v[32:33], v[32:33], 0, s[26:27]
	global_store_dword v[32:33], v34, off
; __device__ __forceinline__ unsigned pk2(float lo, float hi) { unsigned r; asm volatile("v_cvt_pk_bf16_f32 %0, %1, %2" : "=v"(r) : "v"(lo), "v"(hi)); return r; }
;     __device__ __forceinline__ void operator()(const f32x4 (&acc)[2][2][4][2], const Unit& u, int wr, int wc, int fr, int fq) const {
;     ...
;             for (int m = 0; m < 4; ++m) {
;                 const int row = row0 + ai * 128 + m * 16; const size_t ro = (size_t)row * DM + col0;
;                 float s = 0.f;
; #pragma unroll
;                 for (int bj = 0; bj < 2; ++bj)
; #pragma unroll
;                     for (int n = 0; n < 2; ++n) {
;                         const size_t o = ro + bj * 128 + n * 16;
;                         const f32x4 xn = *(const f32x4*)(xo + o) + acc[ai][bj][m][n];
;                         *(f32x4*)(xf + o) = xn;
;                         u32x2 w; w.x = pk2(xn[0], xn[1]); w.y = pk2(xn[2], xn[3]); *(u32x2*)(xb + o) = w;
;                         s += (xn[0] * xn[0] + xn[1] * xn[1]) + (xn[2] * xn[2] + xn[3] * xn[3]);
;                     }
;                 s += __shfl_xor(s, 16); s += __shfl_xor(s, 32);
;                 if (fq == 0) ssq[(size_t)row * 16 + u.pn * 4 + wc] = s;
.LBB0_2190:
	s_or_b64 exec, exec, s[42:43]
	v_add_u32_e32 v32, 0xa0, v138
	s_waitcnt lgkmcnt(0)
	v_ashrrev_i32_e32 v33, 31, v32
	v_lshlrev_b64 v[34:35], 10, v[32:33]
	v_lshl_add_u64 v[38:39], v[34:35], 0, v[136:137]
	v_lshlrev_b64 v[40:41], 2, v[38:39]
	v_lshl_add_u64 v[42:43], s[12:13], 0, v[40:41]
	v_lshl_add_u64 v[38:39], v[38:39], 1, s[22:23]
	v_lshl_add_u64 v[40:41], s[16:17], 0, v[40:41]
	s_waitcnt vmcnt(24)
	v_mov_b32_e32 v34, v198
	v_mov_b32_e32 v35, v199
	v_mov_b32_e32 v36, v200
	v_mov_b32_e32 v37, v201
	v_pk_add_f32 v[30:31], v[30:31], v[36:37]
	v_pk_add_f32 v[28:29], v[28:29], v[34:35]
	global_store_dwordx4 v[40:41], v[28:31], off
	v_cvt_pk_bf16_f32 v34, v28, v29
	v_cvt_pk_bf16_f32 v35, v30, v31
	v_mul_f32_e32 v29, v29, v29
	v_mul_f32_e32 v31, v31, v31
	v_fmac_f32_e32 v29, v28, v28
	v_fmac_f32_e32 v31, v30, v30
	v_add_f32_e32 v28, v29, v31
	s_waitcnt vmcnt(23)
	v_mov_b32_e32 v34, v202
	v_mov_b32_e32 v35, v203
	v_mov_b32_e32 v36, v204
	v_mov_b32_e32 v37, v205
	v_pk_add_f32 v[26:27], v[26:27], v[36:37]
	v_pk_add_f32 v[24:25], v[24:25], v[34:35]
	global_store_dwordx4 v[40:41], v[24:27], off offset:64
	v_cvt_pk_bf16_f32 v34, v24, v25
	v_cvt_pk_bf16_f32 v35, v26, v27
	v_mul_f32_e32 v25, v25, v25
	v_mul_f32_e32 v27, v27, v27
	v_fmac_f32_e32 v25, v24, v24
	v_fmac_f32_e32 v27, v26, v26
	v_add_f32_e32 v24, v25, v27
	v_add_f32_e32 v24, v28, v24
	s_waitcnt vmcnt(22)
	v_mov_b32_e32 v34, v206
	v_mov_b32_e32 v35, v207
	v_mov_b32_e32 v36, v208
	v_mov_b32_e32 v37, v209
	v_pk_add_f32 v[22:23], v[22:23], v[36:37]
	v_pk_add_f32 v[20:21], v[20:21], v[34:35]
	global_store_dwordx4 v[40:41], v[20:23], off offset:512
	v_cvt_pk_bf16_f32 v34, v20, v21
	v_cvt_pk_bf16_f32 v35, v22, v23
	v_mul_f32_e32 v21, v21, v21
	v_mul_f32_e32 v23, v23, v23
	v_fmac_f32_e32 v21, v20, v20
	v_fmac_f32_e32 v23, v22, v22
	v_add_f32_e32 v20, v21, v23
	v_add_f32_e32 v22, v24, v20
	s_waitcnt vmcnt(21)
	v_mov_b32_e32 v34, v210
	v_mov_b32_e32 v35, v211
	v_mov_b32_e32 v36, v212
	v_mov_b32_e32 v37, v213
	v_pk_add_f32 v[20:21], v[18:19], v[36:37]
	v_pk_add_f32 v[18:19], v[16:17], v[34:35]
	v_mul_f32_e32 v17, v21, v21
	v_mul_f32_e32 v16, v19, v19
	v_fmac_f32_e32 v16, v18, v18
	v_fmac_f32_e32 v17, v20, v20
	v_add_f32_e32 v16, v16, v17
	v_add_f32_e32 v16, v22, v16
	ds_bpermute_b32 v17, v116, v16
	global_store_dwordx4 v[40:41], v[18:21], off offset:576
	s_waitcnt lgkmcnt(0)
	v_add_f32_e32 v16, v16, v17
	ds_bpermute_b32 v17, v114, v16
	v_cvt_pk_bf16_f32 v18, v18, v19
	v_cvt_pk_bf16_f32 v19, v20, v21
	s_and_saveexec_b64 s[42:43], s[8:9]
	s_cbranch_execz .LBB0_2192
	s_waitcnt lgkmcnt(0)
	v_add_f32_e32 v18, v16, v17
	v_lshlrev_b64 v[16:17], 6, v[32:33]
	v_lshl_add_u64 v[16:17], s[24:25], 0, v[16:17]
	v_lshl_add_u64 v[16:17], s[40:41], 2, v[16:17]
	s_lshl_b32 s26, s74, 2
	v_lshl_add_u64 v[16:17], v[16:17], 0, s[26:27]
	global_store_dword v[16:17], v18, off
.LBB0_2192:
	s_or_b64 exec, exec, s[42:43]
	v_add_u32_e32 v16, 0xb0, v138
	s_waitcnt lgkmcnt(0)
	v_ashrrev_i32_e32 v17, 31, v16
	v_lshlrev_b64 v[18:19], 10, v[16:17]
	v_lshl_add_u64 v[22:23], v[18:19], 0, v[136:137]
	v_lshlrev_b64 v[24:25], 2, v[22:23]
	v_lshl_add_u64 v[26:27], s[12:13], 0, v[24:25]
	v_lshl_add_u64 v[22:23], v[22:23], 1, s[22:23]
	v_lshl_add_u64 v[24:25], s[16:17], 0, v[24:25]
	s_waitcnt vmcnt(20)
	v_mov_b32_e32 v18, v232
	v_mov_b32_e32 v19, v233
	v_mov_b32_e32 v20, v234
	v_mov_b32_e32 v21, v235
	v_pk_add_f32 v[14:15], v[14:15], v[20:21]
	v_pk_add_f32 v[12:13], v[12:13], v[18:19]
	global_store_dwordx4 v[24:25], v[12:15], off
	v_cvt_pk_bf16_f32 v18, v12, v13
	v_cvt_pk_bf16_f32 v19, v14, v15
	v_mul_f32_e32 v13, v13, v13
	v_mul_f32_e32 v15, v15, v15
	v_fmac_f32_e32 v13, v12, v12
	v_fmac_f32_e32 v15, v14, v14
	v_add_f32_e32 v12, v13, v15
	s_waitcnt vmcnt(19)
	v_mov_b32_e32 v18, v236
	v_mov_b32_e32 v19, v237
	v_mov_b32_e32 v20, v238
	v_mov_b32_e32 v21, v239
	v_pk_add_f32 v[10:11], v[10:11], v[20:21]
	v_pk_add_f32 v[8:9], v[8:9], v[18:19]
	global_store_dwordx4 v[24:25], v[8:11], off offset:64
	v_cvt_pk_bf16_f32 v18, v8, v9
	v_cvt_pk_bf16_f32 v19, v10, v11
	v_mul_f32_e32 v9, v9, v9
	v_mul_f32_e32 v11, v11, v11
	v_fmac_f32_e32 v9, v8, v8
	v_fmac_f32_e32 v11, v10, v10
	v_add_f32_e32 v8, v9, v11
	v_add_f32_e32 v8, v12, v8
	s_waitcnt vmcnt(18)
	v_mov_b32_e32 v18, v240
	v_mov_b32_e32 v19, v241
	v_mov_b32_e32 v20, v242
	v_mov_b32_e32 v21, v243
	v_pk_add_f32 v[6:7], v[6:7], v[20:21]
	v_pk_add_f32 v[4:5], v[4:5], v[18:19]
	global_store_dwordx4 v[24:25], v[4:7], off offset:512
	v_cvt_pk_bf16_f32 v18, v4, v5
	v_cvt_pk_bf16_f32 v19, v6, v7
	v_mul_f32_e32 v5, v5, v5
	v_mul_f32_e32 v7, v7, v7
	v_fmac_f32_e32 v5, v4, v4
	v_fmac_f32_e32 v7, v6, v6
	v_add_f32_e32 v4, v5, v7
	v_add_f32_e32 v6, v8, v4
	s_waitcnt vmcnt(17)
	v_mov_b32_e32 v18, v244
	v_mov_b32_e32 v19, v245
	v_mov_b32_e32 v20, v246
	v_mov_b32_e32 v21, v247
	v_pk_add_f32 v[4:5], v[2:3], v[20:21]
	v_pk_add_f32 v[2:3], v[0:1], v[18:19]
	v_mul_f32_e32 v1, v5, v5
	v_mul_f32_e32 v0, v3, v3
	v_fmac_f32_e32 v0, v2, v2
	v_fmac_f32_e32 v1, v4, v4
	v_add_f32_e32 v0, v0, v1
	v_add_f32_e32 v0, v6, v0
	ds_bpermute_b32 v1, v116, v0
	global_store_dwordx4 v[24:25], v[2:5], off offset:576
	s_waitcnt lgkmcnt(0)
	v_add_f32_e32 v0, v0, v1
	ds_bpermute_b32 v1, v114, v0
	v_cvt_pk_bf16_f32 v2, v2, v3
	v_cvt_pk_bf16_f32 v3, v4, v5
	s_and_saveexec_b64 s[12:13], s[8:9]
	s_cbranch_execz .LBB0_2153
	s_waitcnt lgkmcnt(0)
	v_add_f32_e32 v2, v0, v1
	v_lshlrev_b64 v[0:1], 6, v[16:17]
	v_lshl_add_u64 v[0:1], s[24:25], 0, v[0:1]
	v_lshl_add_u64 v[0:1], s[40:41], 2, v[0:1]
	s_lshl_b32 s26, s74, 2
	v_lshl_add_u64 v[0:1], v[0:1], 0, s[26:27]
	global_store_dword v[0:1], v2, off
	s_branch .LBB0_2153
